# attention loop first half: softmax VALU block moved in front of the LDS-write barrier, plus static priority 1 for waves 4-7
# baseline (speedup 1.0000x reference)
.LBB0_453:
	ds_read_b128 v[66:69], v209 offset:49152
	ds_read_b128 v[70:73], v209 offset:57344
	ds_read_b128 v[232:235], v214 offset:49152
	ds_read_b128 v[236:239], v214 offset:57344
	ds_read_b128 v[200:203], v213 offset:49152
	ds_read_b128 v[204:207], v213 offset:57344
	v_add_f32_e32 v164, 0, v165
	v_add_f32_e32 v164, v179, v164
	s_waitcnt lgkmcnt(5)
	v_mfma_f32_32x32x16_bf16 v[82:97], v[66:69], v[120:123], 0
	v_add_f32_e32 v164, v166, v164
	v_add_f32_e32 v164, v221, v164
	v_add_f32_e32 v164, v178, v164
	v_add_f32_e32 v164, v231, v164
	v_add_f32_e32 v164, v167, v164
	v_add_f32_e32 v164, v177, v164
	v_add_f32_e32 v164, v173, v164
	s_waitcnt lgkmcnt(4)
	v_mfma_f32_32x32x16_bf16 v[66:81], v[70:73], v[120:123], 0
	v_add_f32_e32 v164, v175, v164
	v_add_f32_e32 v164, v174, v164
	v_add_f32_e32 v164, v176, v164
	v_exp_f32_e32 v162, v162
	v_add_f32_e32 v164, v169, v164
	v_exp_f32_e32 v163, v163
	v_add_f32_e32 v164, v171, v164
	s_waitcnt lgkmcnt(3)
	v_mfma_f32_32x32x16_bf16 v[82:97], v[232:235], v[112:115], v[82:97]
	v_exp_f32_e32 v160, v160
	v_add_f32_e32 v164, v170, v164
	v_exp_f32_e32 v161, v161
	v_add_f32_e32 v164, v172, v164
	v_exp_f32_e32 v156, v156
	v_add_f32_e32 v164, v162, v164
	v_exp_f32_e32 v157, v157
	s_waitcnt lgkmcnt(2)
	v_mfma_f32_32x32x16_bf16 v[66:81], v[236:239], v[112:115], v[66:81]
	ds_read_b128 v[232:235], v212 offset:49152
	ds_read_b128 v[236:239], v212 offset:57344
	v_add_f32_e32 v164, v163, v164
	v_exp_f32_e32 v152, v152
	v_add_f32_e32 v164, v160, v164
	v_exp_f32_e32 v153, v153
	v_add_f32_e32 v164, v161, v164
	v_exp_f32_e32 v150, v150
	s_waitcnt lgkmcnt(3)
	v_mfma_f32_32x32x16_bf16 v[82:97], v[200:203], v[128:131], v[82:97]
	v_add_f32_e32 v164, v156, v164
	v_exp_f32_e32 v151, v151
	v_add_f32_e32 v164, v157, v164
	v_exp_f32_e32 v158, v158
	v_add_f32_e32 v164, v152, v164
	v_exp_f32_e32 v159, v159
	v_add_f32_e32 v164, v153, v164
	s_waitcnt lgkmcnt(2)
	v_mfma_f32_32x32x16_bf16 v[66:81], v[204:207], v[128:131], v[66:81]
	ds_read_b128 v[200:203], v211 offset:49152
	ds_read_b128 v[204:207], v211 offset:57344
	v_exp_f32_e32 v154, v154
	v_add_f32_e32 v164, v150, v164
	v_exp_f32_e32 v155, v155
	v_add_f32_e32 v164, v151, v164
	v_exp_f32_e32 v148, v148
	v_add_f32_e32 v164, v158, v164
	s_waitcnt lgkmcnt(3)
	v_mfma_f32_32x32x16_bf16 v[82:97], v[232:235], v[124:127], v[82:97]
	v_exp_f32_e32 v149, v149
	v_add_f32_e32 v164, v159, v164
	v_add_f32_e32 v164, v154, v164
	v_add_f32_e32 v164, v155, v164
	v_add_f32_e32 v164, v148, v164
	v_add_f32_e32 v218, v149, v164
	v_mov_b32_e32 v219, v218
	s_waitcnt lgkmcnt(2)
	v_mfma_f32_32x32x16_bf16 v[66:81], v[236:239], v[124:127], v[66:81]
	ds_read_b128 v[232:235], v210 offset:49152
	ds_read_b128 v[236:239], v210 offset:57344
	v_permlane32_swap_b32_e32 v218, v219
	s_waitcnt lgkmcnt(3)
	v_mfma_f32_32x32x16_bf16 v[82:97], v[200:203], v[116:119], v[82:97]
	s_waitcnt lgkmcnt(2)
	v_mfma_f32_32x32x16_bf16 v[66:81], v[204:207], v[116:119], v[66:81]
	ds_read_b128 v[200:203], v216 offset:49152
	ds_read_b128 v[204:207], v216 offset:57344
	s_waitcnt lgkmcnt(3)
	v_mfma_f32_32x32x16_bf16 v[82:97], v[232:235], v[108:111], v[82:97]
	s_waitcnt lgkmcnt(2)
	v_mfma_f32_32x32x16_bf16 v[66:81], v[236:239], v[108:111], v[66:81]
	ds_read_b128 v[232:235], v215 offset:49152
	ds_read_b128 v[236:239], v215 offset:57344
	s_waitcnt lgkmcnt(3)
	v_mfma_f32_32x32x16_bf16 v[82:97], v[200:203], v[104:107], v[82:97]
	s_waitcnt lgkmcnt(2)
	v_mfma_f32_32x32x16_bf16 v[66:81], v[204:207], v[104:107], v[66:81]
	v_cvt_pk_bf16_f32 v164, v165, v179
	v_cvt_pk_bf16_f32 v165, v166, v221
	v_cvt_pk_bf16_f32 v166, v178, v231
	v_cvt_pk_bf16_f32 v167, v167, v177
	v_cvt_pk_bf16_f32 v220, v173, v175
	v_cvt_pk_bf16_f32 v221, v174, v176
	s_waitcnt lgkmcnt(1)
	v_mfma_f32_32x32x16_bf16 v[82:97], v[232:235], v[100:103], v[82:97]
	v_cvt_pk_bf16_f32 v222, v169, v171
	v_permlane32_swap_b32_e32 v164, v166
	v_cvt_pk_bf16_f32 v223, v170, v172
	v_permlane32_swap_b32_e32 v220, v222
	v_cvt_pk_bf16_f32 v170, v162, v163
	s_waitcnt lgkmcnt(0)
	v_mfma_f32_32x32x16_bf16 v[66:81], v[236:239], v[100:103], v[66:81]
	ds_read_b64_tr_b16 v[232:233], v192 offset:0
	ds_read_b64_tr_b16 v[234:235], v192 offset:0x800
	ds_read_b64_tr_b16 v[236:237], v192 offset:0x1000
	ds_read_b64_tr_b16 v[238:239], v192 offset:0x1800
	ds_read_b64_tr_b16 v[240:241], v192 offset:0x2000
	ds_read_b64_tr_b16 v[242:243], v192 offset:0x2800
	ds_read_b64_tr_b16 v[244:245], v192 offset:0x3000
	ds_read_b64_tr_b16 v[246:247], v192 offset:0x3800
	v_cvt_pk_bf16_f32 v171, v160, v161
	v_cvt_pk_bf16_f32 v172, v156, v157
	v_cvt_pk_bf16_f32 v173, v152, v153
	v_cvt_pk_bf16_f32 v174, v150, v151
	v_cvt_pk_bf16_f32 v175, v158, v159
	v_cvt_pk_bf16_f32 v176, v154, v155
	v_cvt_pk_bf16_f32 v177, v148, v149
	v_permlane32_swap_b32_e32 v165, v167
	v_permlane32_swap_b32_e32 v221, v223
	v_permlane32_swap_b32_e32 v170, v172
	v_permlane32_swap_b32_e32 v171, v173
	v_permlane32_swap_b32_e32 v174, v176
	v_permlane32_swap_b32_e32 v175, v177
	v_add_co_u32_e32 v148, vcc, s1, v180
	s_nop 1
	v_addc_co_u32_e32 v149, vcc, -1, v181, vcc
	v_add_co_u32_e32 v152, vcc, s28, v180
	s_nop 1
	v_addc_co_u32_e32 v153, vcc, -1, v181, vcc
	v_add_co_u32_e32 v156, vcc, s19, v180
	global_load_dwordx4 v[148:151], v[148:149], off
	s_nop 0
	global_load_dwordx4 v[152:155], v[152:153], off
	v_addc_co_u32_e32 v157, vcc, -1, v181, vcc
	v_add_co_u32_e32 v160, vcc, s27, v180
	s_nop 1
	v_addc_co_u32_e32 v161, vcc, -1, v181, vcc
	global_load_dwordx4 v[156:159], v[156:157], off
	s_nop 0
	global_load_dwordx4 v[160:163], v[160:161], off
	s_waitcnt lgkmcnt(0)
	s_nop 0
	v_mfma_f32_32x32x16_bf16 v[2:17], v[164:167], v[232:235], v[2:17]
	ds_read_b64_tr_b16 v[232:233], v192 offset:0x200
	ds_read_b64_tr_b16 v[234:235], v192 offset:0xa00
	v_mfma_f32_32x32x16_bf16 v[2:17], v[220:223], v[236:239], v[2:17]
	ds_read_b64_tr_b16 v[236:237], v192 offset:0x1200
	ds_read_b64_tr_b16 v[238:239], v192 offset:0x1a00
	v_mfma_f32_32x32x16_bf16 v[2:17], v[170:173], v[240:243], v[2:17]
	ds_read_b64_tr_b16 v[240:241], v192 offset:0x2200
	ds_read_b64_tr_b16 v[242:243], v192 offset:0x2a00
	v_mfma_f32_32x32x16_bf16 v[2:17], v[174:177], v[244:247], v[2:17]
	ds_read_b64_tr_b16 v[244:245], v192 offset:0x3200
	ds_read_b64_tr_b16 v[246:247], v192 offset:0x3a00
	s_waitcnt lgkmcnt(0)
	v_mfma_f32_32x32x16_bf16 v[50:65], v[164:167], v[232:235], v[50:65]
	ds_read_b64_tr_b16 v[232:233], v192 offset:0x400
	ds_read_b64_tr_b16 v[234:235], v192 offset:0xc00
	v_mfma_f32_32x32x16_bf16 v[50:65], v[220:223], v[236:239], v[50:65]
	ds_read_b64_tr_b16 v[236:237], v192 offset:0x1400
	ds_read_b64_tr_b16 v[238:239], v192 offset:0x1c00
	v_mfma_f32_32x32x16_bf16 v[50:65], v[170:173], v[240:243], v[50:65]
	ds_read_b64_tr_b16 v[240:241], v192 offset:0x2400
	ds_read_b64_tr_b16 v[242:243], v192 offset:0x2c00
	v_mfma_f32_32x32x16_bf16 v[50:65], v[174:177], v[244:247], v[50:65]
	ds_read_b64_tr_b16 v[244:245], v192 offset:0x3400
	ds_read_b64_tr_b16 v[246:247], v192 offset:0x3c00
	s_waitcnt lgkmcnt(0)
	v_mfma_f32_32x32x16_bf16 v[34:49], v[164:167], v[232:235], v[34:49]
	ds_read_b64_tr_b16 v[232:233], v192 offset:0x600
	ds_read_b64_tr_b16 v[234:235], v192 offset:0xe00
	v_mfma_f32_32x32x16_bf16 v[34:49], v[220:223], v[236:239], v[34:49]
	ds_read_b64_tr_b16 v[236:237], v192 offset:0x1600
	ds_read_b64_tr_b16 v[238:239], v192 offset:0x1e00
	v_mfma_f32_32x32x16_bf16 v[34:49], v[170:173], v[240:243], v[34:49]
	ds_read_b64_tr_b16 v[240:241], v192 offset:0x2600
	ds_read_b64_tr_b16 v[242:243], v192 offset:0x2e00
	v_mfma_f32_32x32x16_bf16 v[34:49], v[174:177], v[244:247], v[34:49]
	ds_read_b64_tr_b16 v[244:245], v192 offset:0x3600
	ds_read_b64_tr_b16 v[246:247], v192 offset:0x3e00
	s_waitcnt lgkmcnt(0)
	v_mfma_f32_32x32x16_bf16 v[18:33], v[164:167], v[232:235], v[18:33]
	v_max_f32_e32 v164, v83, v83
	v_max_f32_e32 v165, v82, v82
	v_max_f32_e32 v164, v165, v164
	v_max3_f32 v164, v164, v84, v85
	v_max3_f32 v164, v164, v86, v87
	v_max3_f32 v164, v164, v88, v89
	v_max3_f32 v164, v164, v90, v91
	v_max3_f32 v164, v164, v92, v93
	v_max3_f32 v164, v164, v94, v95
	v_mfma_f32_32x32x16_bf16 v[18:33], v[220:223], v[236:239], v[18:33]
	v_max3_f32 v164, v164, v96, v97
	v_max3_f32 v164, v164, v66, v67
	v_max3_f32 v164, v164, v68, v69
	v_max3_f32 v164, v164, v70, v71
	v_max3_f32 v164, v164, v72, v73
	v_max3_f32 v164, v164, v74, v75
	v_max3_f32 v164, v164, v76, v77
	v_max3_f32 v164, v164, v78, v79
	v_mfma_f32_32x32x16_bf16 v[18:33], v[170:173], v[240:243], v[18:33]
	v_max3_f32 v164, v164, v80, v81
	v_mov_b32_e32 v165, v164
	s_nop 1
	v_permlane32_swap_b32_e32 v164, v165
	v_max_f32_e32 v165, v165, v165
	v_max_f32_e32 v164, v164, v164
	v_max_f32_e32 v164, v164, v165
	v_sub_f32_e32 v165, v164, v168
	v_cmp_ge_f32_e32 vcc, s0, v165
	v_max_f32_e32 v165, v168, v168
	v_max_f32_e32 v164, v165, v164
	v_mfma_f32_32x32x16_bf16 v[18:33], v[174:177], v[244:247], v[18:33]
	v_sub_f32_e32 v165, v168, v164
	v_mul_f32_e32 v165, 0x3e0293ee, v165
	v_exp_f32_e32 v165, v165
	s_cmp_eq_u64 vcc, exec
	s_cselect_b64 s[42:43], -1, 0
	v_cndmask_b32_e64 v220, v165, 1.0, s[42:43]
	v_cmp_gt_f32_e32 vcc, 1.0, v220
	s_cbranch_vccz .LBB0_457
	s_and_saveexec_b64 s[4:5], s[40:41]
	ds_write_b32 v189, v220 offset:128
	s_or_b64 exec, exec, s[4:5]
	s_waitcnt lgkmcnt(0)
	v_add_u32_e32 v165, v188, v98
	ds_read_b128 v[170:173], v165 offset:224
	ds_read_b128 v[174:177], v165 offset:192
	ds_read_b128 v[232:235], v165 offset:160
	ds_read_b128 v[236:239], v165 offset:128
	s_waitcnt lgkmcnt(3)
	v_pk_mul_f32 v[14:15], v[14:15], v[170:171]
	s_waitcnt lgkmcnt(2)
	v_pk_mul_f32 v[10:11], v[10:11], v[174:175]
	s_waitcnt lgkmcnt(1)
	v_pk_mul_f32 v[6:7], v[6:7], v[232:233]
	v_pk_mul_f32 v[16:17], v[16:17], v[172:173]
	v_pk_mul_f32 v[12:13], v[12:13], v[176:177]
	v_pk_mul_f32 v[8:9], v[8:9], v[234:235]
	s_waitcnt lgkmcnt(0)
	v_pk_mul_f32 v[4:5], v[4:5], v[238:239]
	v_pk_mul_f32 v[2:3], v[2:3], v[236:237]
	v_pk_mul_f32 v[62:63], v[62:63], v[170:171]
	v_pk_mul_f32 v[58:59], v[58:59], v[174:175]
	v_pk_mul_f32 v[54:55], v[54:55], v[232:233]
	v_pk_mul_f32 v[64:65], v[64:65], v[172:173]
	v_pk_mul_f32 v[60:61], v[60:61], v[176:177]
	v_pk_mul_f32 v[56:57], v[56:57], v[234:235]
	v_pk_mul_f32 v[52:53], v[52:53], v[238:239]
	v_pk_mul_f32 v[50:51], v[50:51], v[236:237]
	v_pk_mul_f32 v[46:47], v[46:47], v[170:171]
	v_pk_mul_f32 v[42:43], v[42:43], v[174:175]
	v_pk_mul_f32 v[38:39], v[38:39], v[232:233]
	v_pk_mul_f32 v[48:49], v[48:49], v[172:173]
	v_pk_mul_f32 v[44:45], v[44:45], v[176:177]
	v_pk_mul_f32 v[40:41], v[40:41], v[234:235]
	v_pk_mul_f32 v[36:37], v[36:37], v[238:239]
	v_pk_mul_f32 v[34:35], v[34:35], v[236:237]
	v_pk_mul_f32 v[30:31], v[30:31], v[170:171]
	v_pk_mul_f32 v[26:27], v[26:27], v[174:175]
	v_pk_mul_f32 v[22:23], v[22:23], v[232:233]
	v_pk_mul_f32 v[32:33], v[32:33], v[172:173]
	v_pk_mul_f32 v[28:29], v[28:29], v[176:177]
	v_pk_mul_f32 v[24:25], v[24:25], v[234:235]
	v_pk_mul_f32 v[20:21], v[20:21], v[238:239]
	v_pk_mul_f32 v[18:19], v[18:19], v[236:237]
.LBB0_457:
	v_cndmask_b32_e64 v221, v164, v168, s[42:43]
	v_mul_f32_e32 v222, 0xbe0293ee, v221
	v_fmamk_f32 v82, v82, 0x3e0293ee, v222
	v_fmamk_f32 v83, v83, 0x3e0293ee, v222
	v_fmamk_f32 v84, v84, 0x3e0293ee, v222
	v_fmamk_f32 v85, v85, 0x3e0293ee, v222
	v_fmamk_f32 v86, v86, 0x3e0293ee, v222
	v_fmamk_f32 v87, v87, 0x3e0293ee, v222
	v_fmamk_f32 v88, v88, 0x3e0293ee, v222
	v_fmamk_f32 v89, v89, 0x3e0293ee, v222
	v_fmamk_f32 v90, v90, 0x3e0293ee, v222
	v_fmamk_f32 v91, v91, 0x3e0293ee, v222
	v_fmamk_f32 v92, v92, 0x3e0293ee, v222
	v_fmamk_f32 v93, v93, 0x3e0293ee, v222
	v_fmamk_f32 v94, v94, 0x3e0293ee, v222
	v_fmamk_f32 v95, v95, 0x3e0293ee, v222
	v_fmamk_f32 v96, v96, 0x3e0293ee, v222
	v_fmamk_f32 v97, v97, 0x3e0293ee, v222
	v_exp_f32_e32 v164, v82
	v_exp_f32_e32 v179, v83
	v_exp_f32_e32 v165, v84
	v_exp_f32_e32 v178, v85
	v_exp_f32_e32 v166, v86
	v_exp_f32_e32 v177, v87
	v_exp_f32_e32 v167, v88
	v_exp_f32_e32 v176, v89
	v_exp_f32_e32 v168, v90
	v_exp_f32_e32 v175, v91
	v_exp_f32_e32 v169, v92
	v_exp_f32_e32 v174, v93
	v_exp_f32_e32 v170, v94
	v_exp_f32_e32 v173, v95
	v_exp_f32_e32 v171, v96
	v_exp_f32_e32 v172, v97
	v_fmamk_f32 v238, v66, 0x3e0293ee, v222
	v_fmamk_f32 v239, v67, 0x3e0293ee, v222
	v_fmamk_f32 v240, v68, 0x3e0293ee, v222
	v_fmamk_f32 v241, v69, 0x3e0293ee, v222
	v_fmamk_f32 v242, v70, 0x3e0293ee, v222
	v_fmamk_f32 v231, v71, 0x3e0293ee, v222
	v_fmamk_f32 v232, v72, 0x3e0293ee, v222
	v_fmamk_f32 v233, v73, 0x3e0293ee, v222
	v_fmamk_f32 v234, v74, 0x3e0293ee, v222
	v_fmamk_f32 v235, v75, 0x3e0293ee, v222
	v_fmamk_f32 v236, v76, 0x3e0293ee, v222
	v_fmamk_f32 v237, v77, 0x3e0293ee, v222
	v_fmamk_f32 v223, v78, 0x3e0293ee, v222
	v_fmamk_f32 v243, v79, 0x3e0293ee, v222
	v_fmamk_f32 v244, v80, 0x3e0293ee, v222
	v_fmac_f32_e32 v222, 0x3e0293ee, v81
	s_barrier
	s_waitcnt vmcnt(4)
	s_waitcnt vmcnt(7)
	ds_write_b128 v195, v[132:135]
	s_waitcnt vmcnt(6)
	ds_write_b128 v208, v[140:143]
	s_waitcnt vmcnt(5)
	ds_write_b128 v193, v[136:139] offset:32768
	s_waitcnt vmcnt(4)
	ds_write_b128 v194, v[144:147] offset:32768
	s_waitcnt lgkmcnt(0)
	s_barrier
	ds_read_b128 v[66:69], v209 offset:32768
	ds_read_b128 v[70:73], v209 offset:40960
	ds_read_b128 v[246:249], v214 offset:32768
	ds_read_b128 v[196:199], v214 offset:40960
	ds_read_b128 v[200:203], v213 offset:32768
	ds_read_b128 v[204:207], v213 offset:40960
	v_exp_f32_e32 v231, v231
	v_exp_f32_e32 v232, v232
	s_waitcnt lgkmcnt(5)
	v_mfma_f32_32x32x16_bf16 v[82:97], v[66:69], v[120:123], 0
	v_exp_f32_e32 v233, v233
	v_exp_f32_e32 v234, v234
	v_exp_f32_e32 v235, v235
	v_exp_f32_e32 v236, v236
	v_exp_f32_e32 v237, v237
	s_waitcnt lgkmcnt(4)
	v_mfma_f32_32x32x16_bf16 v[66:81], v[70:73], v[120:123], 0
	s_waitcnt lgkmcnt(3)
	v_mfma_f32_32x32x16_bf16 v[82:97], v[246:249], v[112:115], v[82:97]
	s_waitcnt lgkmcnt(2)
	v_mfma_f32_32x32x16_bf16 v[66:81], v[196:199], v[112:115], v[66:81]
	ds_read_b128 v[196:199], v212 offset:32768
	ds_read_b128 v[246:249], v212 offset:40960
	s_waitcnt lgkmcnt(3)
	v_mfma_f32_32x32x16_bf16 v[82:97], v[200:203], v[128:131], v[82:97]
	s_waitcnt lgkmcnt(2)
	v_mfma_f32_32x32x16_bf16 v[66:81], v[204:207], v[128:131], v[66:81]
	ds_read_b128 v[200:203], v211 offset:32768
	ds_read_b128 v[204:207], v211 offset:40960
	s_waitcnt lgkmcnt(3)
	v_mfma_f32_32x32x16_bf16 v[82:97], v[196:199], v[124:127], v[82:97]
	s_waitcnt lgkmcnt(2)
	v_mfma_f32_32x32x16_bf16 v[66:81], v[246:249], v[124:127], v[66:81]
	ds_read_b128 v[196:199], v210 offset:32768
	ds_read_b128 v[246:249], v210 offset:40960
	s_waitcnt lgkmcnt(3)
	v_mfma_f32_32x32x16_bf16 v[82:97], v[200:203], v[116:119], v[82:97]
	s_waitcnt lgkmcnt(2)
	v_mfma_f32_32x32x16_bf16 v[66:81], v[204:207], v[116:119], v[66:81]
	ds_read_b128 v[200:203], v216 offset:32768
	ds_read_b128 v[204:207], v216 offset:40960
	s_waitcnt lgkmcnt(3)
	v_mfma_f32_32x32x16_bf16 v[82:97], v[196:199], v[108:111], v[82:97]
	s_waitcnt lgkmcnt(2)
	v_mfma_f32_32x32x16_bf16 v[66:81], v[246:249], v[108:111], v[66:81]
	ds_read_b128 v[196:199], v215 offset:32768
	ds_read_b128 v[246:249], v215 offset:40960
	s_waitcnt lgkmcnt(3)
	v_mfma_f32_32x32x16_bf16 v[82:97], v[200:203], v[104:107], v[82:97]
	s_waitcnt lgkmcnt(2)
	v_mfma_f32_32x32x16_bf16 v[66:81], v[204:207], v[104:107], v[66:81]
	s_waitcnt lgkmcnt(1)
	v_mfma_f32_32x32x16_bf16 v[82:97], v[196:199], v[100:103], v[82:97]
	v_exp_f32_e32 v196, v238
	v_exp_f32_e32 v238, v242
	v_exp_f32_e32 v242, v222
	v_add_f32_e32 v222, 0, v164
	v_add_f32_e32 v222, v179, v222
	v_add_f32_e32 v222, v165, v222
	v_add_f32_e32 v222, v178, v222
	v_add_f32_e32 v222, v166, v222
	v_add_f32_e32 v222, v177, v222
	v_add_f32_e32 v222, v167, v222
	v_add_f32_e32 v222, v176, v222
	v_add_f32_e32 v222, v168, v222
	v_add_f32_e32 v222, v175, v222
	v_add_f32_e32 v222, v169, v222
	v_add_f32_e32 v222, v174, v222
	v_add_f32_e32 v222, v170, v222
	v_exp_f32_e32 v197, v239
	v_add_f32_e32 v222, v173, v222
	v_exp_f32_e32 v198, v240
	v_add_f32_e32 v222, v171, v222
	v_exp_f32_e32 v199, v241
	v_add_f32_e32 v222, v172, v222
	v_add_f32_e32 v222, v196, v222
	v_add_f32_e32 v222, v197, v222
	v_add_f32_e32 v222, v198, v222
	v_add_f32_e32 v222, v199, v222
	v_add_f32_e32 v222, v238, v222
	v_add_f32_e32 v222, v231, v222
	v_add_f32_e32 v222, v232, v222
	v_add_f32_e32 v222, v233, v222
	v_exp_f32_e32 v239, v223
	v_add_f32_e32 v222, v234, v222
	v_exp_f32_e32 v240, v243
	v_add_f32_e32 v222, v235, v222
	s_waitcnt lgkmcnt(0)
	v_mfma_f32_32x32x16_bf16 v[66:81], v[246:249], v[100:103], v[66:81]
	v_exp_f32_e32 v241, v244
	v_add_f32_e32 v222, v236, v222
	v_add_f32_e32 v222, v237, v222
	v_add_f32_e32 v222, v239, v222
	v_add_f32_e32 v222, v240, v222
	v_add_f32_e32 v222, v241, v222
	v_add_f32_e32 v222, v242, v222
	v_mov_b32_e32 v223, v222
	v_cvt_pk_bf16_f32 v164, v164, v179
	v_cvt_pk_bf16_f32 v165, v165, v178
	v_cvt_pk_bf16_f32 v166, v166, v177
	v_cvt_pk_bf16_f32 v167, v167, v176
	v_cvt_pk_bf16_f32 v168, v168, v175
	v_cvt_pk_bf16_f32 v169, v169, v174
	v_cvt_pk_bf16_f32 v170, v170, v173
	v_cvt_pk_bf16_f32 v171, v171, v172
	v_cvt_pk_bf16_f32 v172, v196, v197
	v_cvt_pk_bf16_f32 v173, v198, v199
	v_cvt_pk_bf16_f32 v174, v238, v231
	v_cvt_pk_bf16_f32 v175, v232, v233
	v_cvt_pk_bf16_f32 v176, v234, v235
	v_cvt_pk_bf16_f32 v177, v236, v237
	v_cvt_pk_bf16_f32 v178, v239, v240
	v_cvt_pk_bf16_f32 v179, v241, v242
	s_nop 1
	v_permlane32_swap_b32_e32 v222, v223
	v_permlane32_swap_b32_e32 v164, v166
	v_permlane32_swap_b32_e32 v165, v167
	v_permlane32_swap_b32_e32 v168, v170
	v_permlane32_swap_b32_e32 v169, v171
	v_permlane32_swap_b32_e32 v172, v174
	v_permlane32_swap_b32_e32 v173, v175
	v_permlane32_swap_b32_e32 v176, v178
	v_permlane32_swap_b32_e32 v177, v179
	s_cmp_gt_u32 s6, 64
	s_cselect_b64 s[4:5], -1, 0
	s_and_b64 vcc, exec, s[4:5]
	s_cbranch_vccnz .LBB0_459
	v_add_co_u32_e32 v132, vcc, 0xffffc000, v180
	s_nop 1
	v_addc_co_u32_e32 v133, vcc, -1, v181, vcc
	v_add_co_u32_e32 v136, vcc, 0xff77c000, v180
	s_nop 1
	v_addc_co_u32_e32 v137, vcc, -1, v181, vcc
	v_add_co_u32_e32 v144, vcc, 0xff780000, v180
	global_load_dwordx4 v[132:135], v[132:133], off
	s_nop 0
	global_load_dwordx4 v[136:139], v[136:137], off
	v_addc_co_u32_e32 v145, vcc, -1, v181, vcc
	global_load_dwordx4 v[140:143], v[180:181], off
	s_nop 0
	global_load_dwordx4 v[144:147], v[144:145], off
